# P5 k-loop: removed the two compiler-inserted lgkmcnt(0) between the A-fragment and B-fragment ds_reads
# speedup vs baseline: 1.0019x; 1.0019x over previous
.Lq5_r1:
	s_mov_b64 exec, -1
	v_lshl_add_u64 v[2:3], s[34:35], 0, v[200:201]
	s_add_i32 m0, s48, 0xc000
	ds_read_b128 v[188:191], v216
	ds_read_b128 v[192:195], v216 offset:1024
	ds_read_b128 v[180:183], v216 offset:2048
	ds_read_b128 v[184:187], v216 offset:3072
	ds_read_b128 v[172:175], v216 offset:4096
	ds_read_b128 v[176:179], v216 offset:5120
	ds_read_b128 v[164:167], v216 offset:6144
	ds_read_b128 v[168:171], v216 offset:7168
	s_mov_b64 exec, s[26:27]
	s_cbranch_execz .Lq5_s1
	global_load_lds_dwordx4 v[2:3], off

.Lq5_r3:
	s_mov_b64 exec, -1
	s_add_u32 s58, s58, 0x80000
	s_addc_u32 s59, s59, 0
	s_mov_b32 m0, s62
	v_lshl_add_u64 v[218:219], s[58:59], 0, v[198:199]
	ds_read_b128 v[188:191], v216 offset:32768
	ds_read_b128 v[192:195], v216 offset:33792
	ds_read_b128 v[180:183], v216 offset:34816
	ds_read_b128 v[184:187], v216 offset:35840
	ds_read_b128 v[172:175], v216 offset:36864
	ds_read_b128 v[176:179], v216 offset:37888
	ds_read_b128 v[164:167], v216 offset:38912
	ds_read_b128 v[168:171], v216 offset:39936
	s_mov_b64 exec, s[26:27]
	s_cbranch_execz .Lq5_s5
	global_load_lds_dwordx4 v[218:219], off
